# scan main loop: all LDS fragment reads of a step's 20 MFMAs issued in groups ahead of use (counted lgkmcnt) instead of read, wait 0, mfma
# speedup vs baseline: 1.0226x; 1.0021x over previous
; #define LAS __attribute__((address_space(3)))
; __device__ __forceinline__ void scan_phase(const Params& p, LAS unsigned char* lds) {
;     ...
;             f32x4 acc[5];
; #pragma unroll
;             for (int nb = 0; nb < 5; ++nb) acc[nb] = (f32x4){0.f, 0.f, 0.f, 0.f};
; #pragma unroll
;             for (int kk = 0; kk < 4; ++kk) { const bf16x8 a = *(const LAS bf16x8*)(kT + (16 * wid + fr) * 136 + kk * 32 + fq * 8);
; #pragma unroll
;                 for (int nb = 0; nb < 5; ++nb) { const bf16x8 bv = *(const LAS bf16x8*)(wvT + (nb * 16 + fr) * 136 + kk * 32 + fq * 8);
;                     acc[nb] = __builtin_amdgcn_mfma_f32_16x16x32_bf16(a, bv, acc[nb], 0, 0, 0); } }
; #pragma unroll
;             for (int nb = 0; nb < 5; ++nb) st[nb] = st[nb] * decay + acc[nb];
.LBB0_1413:
	v_lshl_add_u32 v45, v71, 1, s80
	v_add_u32_e32 v59, v45, v70
	v_add_u32_e32 v45, v45, v92
	ds_read_b128 v[110:113], v59
	ds_read_b128 v[114:117], v45 offset:34816
	ds_read_b128 v[118:121], v45 offset:39168
	ds_read_b128 v[122:125], v45 offset:43520
	ds_read_b128 v[126:129], v45 offset:47872
	ds_read_b128 v[130:133], v45 offset:52224
	ds_read_b128 v[152:155], v59 offset:64
	ds_read_b128 v[156:159], v45 offset:34880
	ds_read_b128 v[160:163], v45 offset:39232
	ds_read_b128 v[164:167], v45 offset:43584
	ds_read_b128 v[168:171], v45 offset:47936
	ds_read_b128 v[172:175], v45 offset:52288
	s_add_i32 s67, s67, 16
	s_add_i32 s24, s24, -1
	v_add_u32_e32 v65, 0x200, v65
	s_cmp_eq_u32 s70, 31
	s_waitcnt lgkmcnt(10)
	v_mfma_f32_16x16x32_bf16 v[114:117], v[110:113], v[114:117], 0
	s_waitcnt lgkmcnt(9)
	v_mfma_f32_16x16x32_bf16 v[118:121], v[110:113], v[118:121], 0
	s_waitcnt lgkmcnt(8)
	v_mfma_f32_16x16x32_bf16 v[122:125], v[110:113], v[122:125], 0
	s_waitcnt lgkmcnt(7)
	v_mfma_f32_16x16x32_bf16 v[126:129], v[110:113], v[126:129], 0
	s_waitcnt lgkmcnt(6)
	v_mfma_f32_16x16x32_bf16 v[110:113], v[110:113], v[130:133], 0
	ds_read_b128 v[176:179], v59 offset:128
	ds_read_b128 v[180:183], v45 offset:34944
	ds_read_b128 v[184:187], v45 offset:39296
	ds_read_b128 v[188:191], v45 offset:43648
	ds_read_b128 v[192:195], v45 offset:48000
	ds_read_b128 v[196:199], v45 offset:52352
	s_waitcnt lgkmcnt(10)
	v_mfma_f32_16x16x32_bf16 v[114:117], v[152:155], v[156:159], v[114:117]
	s_waitcnt lgkmcnt(9)
	v_mfma_f32_16x16x32_bf16 v[118:121], v[152:155], v[160:163], v[118:121]
	s_waitcnt lgkmcnt(8)
	v_mfma_f32_16x16x32_bf16 v[122:125], v[152:155], v[164:167], v[122:125]
	s_waitcnt lgkmcnt(7)
	v_mfma_f32_16x16x32_bf16 v[126:129], v[152:155], v[168:171], v[126:129]
	s_waitcnt lgkmcnt(6)
	v_mfma_f32_16x16x32_bf16 v[110:113], v[152:155], v[172:175], v[110:113]
	ds_read_b128 v[200:203], v59 offset:192
	ds_read_b128 v[204:207], v45 offset:35008
	ds_read_b128 v[208:211], v45 offset:39360
	ds_read_b128 v[212:215], v45 offset:43712
	ds_read_b128 v[216:219], v45 offset:48064
	ds_read_b128 v[220:223], v45 offset:52416
	s_waitcnt lgkmcnt(10)
	v_mfma_f32_16x16x32_bf16 v[114:117], v[176:179], v[180:183], v[114:117]
	s_waitcnt lgkmcnt(9)
	v_mfma_f32_16x16x32_bf16 v[118:121], v[176:179], v[184:187], v[118:121]
	s_waitcnt lgkmcnt(8)
	v_mfma_f32_16x16x32_bf16 v[122:125], v[176:179], v[188:191], v[122:125]
	s_waitcnt lgkmcnt(7)
	v_mfma_f32_16x16x32_bf16 v[126:129], v[176:179], v[192:195], v[126:129]
	s_waitcnt lgkmcnt(6)
	v_mfma_f32_16x16x32_bf16 v[110:113], v[176:179], v[196:199], v[110:113]
	s_waitcnt lgkmcnt(4)
	v_mfma_f32_16x16x32_bf16 v[114:117], v[200:203], v[204:207], v[114:117]
	s_waitcnt lgkmcnt(3)
	v_mfma_f32_16x16x32_bf16 v[118:121], v[200:203], v[208:211], v[118:121]
	s_waitcnt lgkmcnt(2)
	v_mfma_f32_16x16x32_bf16 v[122:125], v[200:203], v[212:215], v[122:125]
	s_waitcnt lgkmcnt(1)
	v_mfma_f32_16x16x32_bf16 v[126:129], v[200:203], v[216:219], v[126:129]
	s_waitcnt lgkmcnt(0)
	v_mfma_f32_16x16x32_bf16 v[110:113], v[200:203], v[220:223], v[110:113]
	s_nop 7
	v_pk_fma_f32 v[40:41], v[40:41], v[66:67], v[116:117] op_sel_hi:[1,0,1]
	v_pk_fma_f32 v[42:43], v[42:43], v[66:67], v[114:115] op_sel_hi:[1,0,1]
	v_pk_fma_f32 v[36:37], v[36:37], v[66:67], v[120:121] op_sel_hi:[1,0,1]
	v_pk_fma_f32 v[38:39], v[38:39], v[66:67], v[118:119] op_sel_hi:[1,0,1]
	v_pk_fma_f32 v[32:33], v[32:33], v[66:67], v[124:125] op_sel_hi:[1,0,1]
	v_pk_fma_f32 v[34:35], v[34:35], v[66:67], v[122:123] op_sel_hi:[1,0,1]
	v_fma_f32 v28, v28, v66, v128
	v_fma_f32 v29, v29, v66, v129
	v_pk_fma_f32 v[30:31], v[30:31], v[66:67], v[126:127] op_sel_hi:[1,0,1]
	v_pk_fma_f32 v[24:25], v[24:25], v[66:67], v[112:113] op_sel_hi:[1,0,1]
	v_pk_fma_f32 v[26:27], v[26:27], v[66:67], v[110:111] op_sel_hi:[1,0,1]
	s_cbranch_scc1 .LBB0_1421
